# matrix-core solver: deeper LDS read pipelining and two accumulators in the diagonal-block inverse
# speedup vs baseline: 1.0509x; 1.0018x over previous
; #define LAS __attribute__((address_space(3)))
; __device__ __forceinline__ void rw_phaseA(LAS unsigned char* lds, const RwCtx& X, int item) {
;     ...
;     if (tid_s < 128) {
;         float x[64];
;         int zv = 0; asm volatile("" : "+v"(zv));
;         const LAS float* LABv = LAB + zv;
; #pragma unroll
;         for (int i = 0; i < 64; ++i) x[i] = XS[i * 129 + tid_s];
; #pragma unroll
;         for (int tt = 1; tt < 64; ++tt) { float a = x[tt];
; #pragma unroll
;             for (int s4 = 0; s4 < (tt + 3) / 4; ++s4) { const f32x4 l4 = *(const LAS f32x4*)(LABv + tt * 68 + s4 * 4);
;                 a += l4[0] * x[s4 * 4]; if (s4 * 4 + 1 < tt) a += l4[1] * x[s4 * 4 + 1]; if (s4 * 4 + 2 < tt) a += l4[2] * x[s4 * 4 + 2]; if (s4 * 4 + 3 < tt) a += l4[3] * x[s4 * 4 + 3]; }
;             x[tt] = a;
.LBB0_801:
	s_or_b64 exec, exec, s[0:1]
	v_cmp_lt_i32_e32 vcc, v18, v27
	s_waitcnt lgkmcnt(5)
	v_lshlrev_b32_e32 v5, 2, v18
	v_add3_u32 v6, s88, v30, v5
	v_cndmask_b32_e32 v4, 0, v14, vcc
	v_cmp_le_i32_e32 vcc, v18, v27
	ds_write_b32 v6, v4
	v_add3_u32 v6, s88, v19, v5
	v_cndmask_b32_e32 v4, 0, v15, vcc
	v_cmp_lt_i32_e32 vcc, v18, v31
	ds_write_b32 v6, v4
	v_add3_u32 v6, s88, v20, v5
	v_cndmask_b32_e32 v4, 0, v16, vcc
	v_cmp_lt_i32_e32 vcc, v18, v32
	ds_write_b32 v6, v4
	v_add3_u32 v5, s88, v21, v5
	v_cndmask_b32_e32 v4, 0, v17, vcc
	ds_write_b32 v5, v4
	v_or_b32_e32 v4, v34, v29
	v_cmp_lt_i32_e32 vcc, v4, v26
	v_or_b32_e32 v5, 1, v4
	v_mad_u32_u24 v14, v25, s91, v22
	v_cndmask_b32_e32 v0, 0, v0, vcc
	v_cmp_lt_i32_e32 vcc, v5, v26
	v_or_b32_e32 v5, 2, v4
	v_or_b32_e32 v4, 3, v4
	v_cndmask_b32_e32 v1, 0, v1, vcc
	v_cmp_lt_i32_e32 vcc, v5, v26
	v_cvt_pk_bf16_f32 v0, v0, v1
	s_movk_i32 s0, 0x204
	v_cndmask_b32_e32 v2, 0, v2, vcc
	v_cmp_lt_i32_e32 vcc, v4, v26
	v_add_u32_e32 v4, v28, v24
	v_lshlrev_b32_e32 v8, 2, v8
	v_cndmask_b32_e32 v3, 0, v3, vcc
	v_cvt_pk_bf16_f32 v1, v2, v3
	ds_write_b64 v33, v[0:1] offset:32
	s_waitcnt lgkmcnt(0)
	s_barrier
	ds_read_b128 v[0:3], v4
	ds_read_b128 v[4:7], v4 offset:64
	ds_read_b128 v[10:13], v14 offset:46080
	ds_read_b128 v[14:17], v14 offset:46144
	s_waitcnt lgkmcnt(1)
	v_mfma_f32_16x16x32_bf16 v[10:13], v[0:3], v[10:13], 0
	v_mov_b32_e32 v247, v226
	s_waitcnt lgkmcnt(0)
	v_mfma_f32_16x16x32_bf16 v[10:13], v[4:7], v[14:17], v[10:13]
	v_mul_lo_u32 v14, v27, s0
	v_add_u32_e32 v14, 0, v14
	v_lshlrev_b32_e32 v15, 2, v23
	v_add3_u32 v8, v14, v15, v8
	s_nop 3
	ds_write_b32 v8, v10 offset:55552
	ds_write_b32 v8, v11 offset:56068
	ds_write_b32 v8, v12 offset:56584
	ds_write_b32 v8, v13 offset:57100
	v_mad_u32_u24 v14, v18, s91, v22
	ds_read_b128 v[10:13], v14 offset:46080
	ds_read_b128 v[14:17], v14 offset:46144
	s_waitcnt lgkmcnt(1)
	v_mfma_f32_16x16x32_bf16 v[0:3], v[0:3], v[10:13], 0
	s_movk_i32 s0, 0x80
	s_waitcnt lgkmcnt(0)
	v_mfma_f32_16x16x32_bf16 v[0:3], v[4:7], v[14:17], v[0:3]
	s_nop 7
	ds_write_b32 v8, v0 offset:55616
	ds_write_b32 v8, v1 offset:56132
	ds_write_b32 v8, v2 offset:56648
	ds_write_b32 v8, v3 offset:57164
	s_waitcnt lgkmcnt(0)
	s_barrier
	s_nop 0
	v_and_b32_e32 v0, 15, v247
	v_bfe_u32 v1, v247, 4, 2
	v_lshrrev_b32_e32 v2, 6, v247
	v_mul_u32_u24_e32 v3, 4416, v1
	v_add_u32_e32 v3, 0x15900, v3
	v_mul_u32_u24_e32 v4, 2064, v1
	v_lshl_add_u32 v11, v2, 4, v0
	v_lshl_add_u32 v4, v11, 2, v4
	v_add_u32_e32 v4, 0xd800, v4
	v_mul_u32_u24_e32 v5, 272, v0
	v_lshl_add_u32 v5, v1, 4, v5
	v_add_u32_e32 v5, 0x15900, v5
	ds_read_b32 v64, v4 offset:0
	ds_read_b32 v65, v4 offset:516
	ds_read_b32 v66, v4 offset:1032
	ds_read_b32 v67, v4 offset:1548
	ds_read_b32 v68, v4 offset:8256
	ds_read_b32 v69, v4 offset:8772
	ds_read_b32 v70, v4 offset:9288
	ds_read_b32 v71, v4 offset:9804
	ds_read_b32 v72, v4 offset:16512
	ds_read_b32 v73, v4 offset:17028
	ds_read_b32 v74, v4 offset:17544
	ds_read_b32 v75, v4 offset:18060
	ds_read_b32 v76, v4 offset:24768
	ds_read_b32 v77, v4 offset:25284
	ds_read_b32 v78, v4 offset:25800
	ds_read_b32 v79, v4 offset:26316
	ds_read_b128 v[96:99], v5 offset:4352
	ds_read_b128 v[100:103], v5 offset:8704
	ds_read_b128 v[104:107], v5 offset:8768
	ds_read_b128 v[108:111], v5 offset:13056
	ds_read_b128 v[112:115], v5 offset:13120
	ds_read_b128 v[116:119], v5 offset:13184
	v_cmp_eq_u32_e32 vcc, 0, v0
	s_nop 1
	v_cndmask_b32_e64 v16, 0, 1.0, vcc
	v_cmp_eq_u32_e32 vcc, 1, v0
	s_nop 1
	v_cndmask_b32_e64 v17, 0, 1.0, vcc
	v_cmp_eq_u32_e32 vcc, 2, v0
	s_nop 1
	v_cndmask_b32_e64 v18, 0, 1.0, vcc
	v_cmp_eq_u32_e32 vcc, 3, v0
	s_nop 1
	v_cndmask_b32_e64 v19, 0, 1.0, vcc
	v_cmp_eq_u32_e32 vcc, 4, v0
	s_nop 1
	v_cndmask_b32_e64 v20, 0, 1.0, vcc
	v_cmp_eq_u32_e32 vcc, 5, v0
	s_nop 1
	v_cndmask_b32_e64 v21, 0, 1.0, vcc
	v_cmp_eq_u32_e32 vcc, 6, v0
	s_nop 1
	v_cndmask_b32_e64 v22, 0, 1.0, vcc
	v_cmp_eq_u32_e32 vcc, 7, v0
	s_nop 1
	v_cndmask_b32_e64 v23, 0, 1.0, vcc
	v_cmp_eq_u32_e32 vcc, 8, v0
	s_nop 1
	v_cndmask_b32_e64 v24, 0, 1.0, vcc
	v_cmp_eq_u32_e32 vcc, 9, v0
	s_nop 1
	v_cndmask_b32_e64 v25, 0, 1.0, vcc
	v_cmp_eq_u32_e32 vcc, 10, v0
	s_nop 1
	v_cndmask_b32_e64 v26, 0, 1.0, vcc
	v_cmp_eq_u32_e32 vcc, 11, v0
	s_nop 1
	v_cndmask_b32_e64 v27, 0, 1.0, vcc
	v_cmp_eq_u32_e32 vcc, 12, v0
	s_nop 1
	v_cndmask_b32_e64 v28, 0, 1.0, vcc
	v_cmp_eq_u32_e32 vcc, 13, v0
	s_nop 1
	v_cndmask_b32_e64 v29, 0, 1.0, vcc
	v_cmp_eq_u32_e32 vcc, 14, v0
	s_nop 1
	v_cndmask_b32_e64 v30, 0, 1.0, vcc
	v_cmp_eq_u32_e32 vcc, 15, v0
	s_nop 1
	v_cndmask_b32_e64 v31, 0, 1.0, vcc
	ds_read_b128 v[48:51], v3 offset:272
	ds_read_b128 v[156:159], v3 offset:544
	ds_read_b128 v[32:35], v3 offset:816
	s_waitcnt lgkmcnt(2)
	v_fmac_f32_e32 v17, v48, v16
	ds_read_b128 v[48:51], v3 offset:1088
	s_waitcnt lgkmcnt(2)
	v_fmac_f32_e32 v18, v156, v16
	v_fmac_f32_e32 v18, v157, v17
	ds_read_b128 v[156:159], v3 offset:1360
	ds_read_b128 v[160:163], v3 offset:1376
	s_waitcnt lgkmcnt(3)
	v_fmac_f32_e32 v19, v32, v16
	v_fmac_f32_e32 v19, v33, v17
	v_fmac_f32_e32 v19, v34, v18
	ds_read_b128 v[32:35], v3 offset:1632
	ds_read_b128 v[36:39], v3 offset:1648
	s_waitcnt lgkmcnt(4)
	v_fmac_f32_e32 v20, v48, v16
	v_mul_f32_e32 v13, v49, v17
	v_fmac_f32_e32 v20, v50, v18
	v_fmac_f32_e32 v13, v51, v19
	v_add_f32_e32 v20, v20, v13
	ds_read_b128 v[48:51], v3 offset:1904
	ds_read_b128 v[52:55], v3 offset:1920
	s_waitcnt lgkmcnt(4)
	v_fmac_f32_e32 v21, v156, v16
	v_mul_f32_e32 v13, v157, v17
	v_fmac_f32_e32 v21, v158, v18
	v_fmac_f32_e32 v13, v159, v19
	v_fmac_f32_e32 v21, v160, v20
	v_add_f32_e32 v21, v21, v13
	ds_read_b128 v[156:159], v3 offset:2176
	ds_read_b128 v[160:163], v3 offset:2192
	s_waitcnt lgkmcnt(4)
; #define LAS __attribute__((address_space(3)))
; __device__ __forceinline__ void rw_phaseA(LAS unsigned char* lds, const RwCtx& X, int item) {
;     ...
;     if (tid_s < 128) {
;         float x[64];
;         int zv = 0; asm volatile("" : "+v"(zv));
;         const LAS float* LABv = LAB + zv;
; #pragma unroll
;         for (int i = 0; i < 64; ++i) x[i] = XS[i * 129 + tid_s];
; #pragma unroll
;         for (int tt = 1; tt < 64; ++tt) { float a = x[tt];
; #pragma unroll
;             for (int s4 = 0; s4 < (tt + 3) / 4; ++s4) { const f32x4 l4 = *(const LAS f32x4*)(LABv + tt * 68 + s4 * 4);
;                 a += l4[0] * x[s4 * 4]; if (s4 * 4 + 1 < tt) a += l4[1] * x[s4 * 4 + 1]; if (s4 * 4 + 2 < tt) a += l4[2] * x[s4 * 4 + 2]; if (s4 * 4 + 3 < tt) a += l4[3] * x[s4 * 4 + 3]; }
;             x[tt] = a;
	v_fmac_f32_e32 v22, v32, v16
	v_mul_f32_e32 v13, v33, v17
	v_fmac_f32_e32 v22, v34, v18
	v_fmac_f32_e32 v13, v35, v19
	v_fmac_f32_e32 v22, v36, v20
	v_fmac_f32_e32 v13, v37, v21
	v_add_f32_e32 v22, v22, v13
	ds_read_b128 v[32:35], v3 offset:2448
	ds_read_b128 v[36:39], v3 offset:2464
	ds_read_b128 v[40:43], v3 offset:2480
	s_waitcnt lgkmcnt(5)
	v_fmac_f32_e32 v23, v48, v16
	v_mul_f32_e32 v13, v49, v17
	v_fmac_f32_e32 v23, v50, v18
	v_fmac_f32_e32 v13, v51, v19
	v_fmac_f32_e32 v23, v52, v20
	v_fmac_f32_e32 v13, v53, v21
	v_fmac_f32_e32 v23, v54, v22
	v_add_f32_e32 v23, v23, v13
	ds_read_b128 v[48:51], v3 offset:2720
	ds_read_b128 v[52:55], v3 offset:2736
	ds_read_b128 v[56:59], v3 offset:2752
	s_waitcnt lgkmcnt(6)
	v_fmac_f32_e32 v24, v156, v16
	v_mul_f32_e32 v13, v157, v17
	v_fmac_f32_e32 v24, v158, v18
	v_fmac_f32_e32 v13, v159, v19
	v_fmac_f32_e32 v24, v160, v20
	v_fmac_f32_e32 v13, v161, v21
	v_fmac_f32_e32 v24, v162, v22
	v_fmac_f32_e32 v13, v163, v23
	v_add_f32_e32 v24, v24, v13
	ds_read_b128 v[156:159], v3 offset:2992
	ds_read_b128 v[160:163], v3 offset:3008
	ds_read_b128 v[164:167], v3 offset:3024
	s_waitcnt lgkmcnt(6)
	v_fmac_f32_e32 v25, v32, v16
	v_mul_f32_e32 v13, v33, v17
	v_fmac_f32_e32 v25, v34, v18
	v_fmac_f32_e32 v13, v35, v19
	v_fmac_f32_e32 v25, v36, v20
	v_fmac_f32_e32 v13, v37, v21
	v_fmac_f32_e32 v25, v38, v22
	v_fmac_f32_e32 v13, v39, v23
	v_fmac_f32_e32 v25, v40, v24
	v_add_f32_e32 v25, v25, v13
	ds_read_b128 v[32:35], v3 offset:3264
	ds_read_b128 v[36:39], v3 offset:3280
	ds_read_b128 v[40:43], v3 offset:3296
	s_waitcnt lgkmcnt(6)
	v_fmac_f32_e32 v26, v48, v16
	v_mul_f32_e32 v13, v49, v17
	v_fmac_f32_e32 v26, v50, v18
	v_fmac_f32_e32 v13, v51, v19
	v_fmac_f32_e32 v26, v52, v20
	v_fmac_f32_e32 v13, v53, v21
	v_fmac_f32_e32 v26, v54, v22
	v_fmac_f32_e32 v13, v55, v23
	v_fmac_f32_e32 v26, v56, v24
	v_fmac_f32_e32 v13, v57, v25
	v_add_f32_e32 v26, v26, v13
	ds_read_b128 v[48:51], v3 offset:3536
	ds_read_b128 v[52:55], v3 offset:3552
	ds_read_b128 v[56:59], v3 offset:3568
	ds_read_b128 v[60:63], v3 offset:3584
	s_waitcnt lgkmcnt(7)
	v_fmac_f32_e32 v27, v156, v16
	v_mul_f32_e32 v13, v157, v17
	v_fmac_f32_e32 v27, v158, v18
	v_fmac_f32_e32 v13, v159, v19
	v_fmac_f32_e32 v27, v160, v20
	v_fmac_f32_e32 v13, v161, v21
	v_fmac_f32_e32 v27, v162, v22
	v_fmac_f32_e32 v13, v163, v23
	v_fmac_f32_e32 v27, v164, v24
	v_fmac_f32_e32 v13, v165, v25
	v_fmac_f32_e32 v27, v166, v26
	v_add_f32_e32 v27, v27, v13
	ds_read_b128 v[156:159], v3 offset:3808
	ds_read_b128 v[160:163], v3 offset:3824
	ds_read_b128 v[164:167], v3 offset:3840
	ds_read_b128 v[168:171], v3 offset:3856
	s_waitcnt lgkmcnt(8)
	v_fmac_f32_e32 v28, v32, v16
	v_mul_f32_e32 v13, v33, v17
	v_fmac_f32_e32 v28, v34, v18
	v_fmac_f32_e32 v13, v35, v19
	v_fmac_f32_e32 v28, v36, v20
	v_fmac_f32_e32 v13, v37, v21
	v_fmac_f32_e32 v28, v38, v22
	v_fmac_f32_e32 v13, v39, v23
	v_fmac_f32_e32 v28, v40, v24
	v_fmac_f32_e32 v13, v41, v25
	v_fmac_f32_e32 v28, v42, v26
	v_fmac_f32_e32 v13, v43, v27
	v_add_f32_e32 v28, v28, v13
	ds_read_b128 v[32:35], v3 offset:4080
	ds_read_b128 v[36:39], v3 offset:4096
	ds_read_b128 v[40:43], v3 offset:4112
	ds_read_b128 v[44:47], v3 offset:4128
	s_waitcnt lgkmcnt(8)
	v_fmac_f32_e32 v29, v48, v16
	v_mul_f32_e32 v13, v49, v17
	v_fmac_f32_e32 v29, v50, v18
	v_fmac_f32_e32 v13, v51, v19
	v_fmac_f32_e32 v29, v52, v20
	v_fmac_f32_e32 v13, v53, v21
	v_fmac_f32_e32 v29, v54, v22
	v_fmac_f32_e32 v13, v55, v23
	v_fmac_f32_e32 v29, v56, v24
	v_fmac_f32_e32 v13, v57, v25
	v_fmac_f32_e32 v29, v58, v26
	v_fmac_f32_e32 v13, v59, v27
	v_fmac_f32_e32 v29, v60, v28
	v_add_f32_e32 v29, v29, v13
	s_waitcnt lgkmcnt(4)
	v_fmac_f32_e32 v30, v156, v16
	v_mul_f32_e32 v13, v157, v17
	v_fmac_f32_e32 v30, v158, v18
	v_fmac_f32_e32 v13, v159, v19
	v_fmac_f32_e32 v30, v160, v20
	v_fmac_f32_e32 v13, v161, v21
	v_fmac_f32_e32 v30, v162, v22
	v_fmac_f32_e32 v13, v163, v23
	v_fmac_f32_e32 v30, v164, v24
	v_fmac_f32_e32 v13, v165, v25
	v_fmac_f32_e32 v30, v166, v26
	v_fmac_f32_e32 v13, v167, v27
	v_fmac_f32_e32 v30, v168, v28
	v_fmac_f32_e32 v13, v169, v29
	v_add_f32_e32 v30, v30, v13
	s_waitcnt lgkmcnt(0)
; #define LAS __attribute__((address_space(3)))
; __device__ __forceinline__ unsigned cvt_pk_bf16(float lo, float hi) { const bf16x2_t r = __builtin_convertvector((f32x2){lo, hi}, bf16x2_t); return __builtin_bit_cast(unsigned, r); }
; __device__ __forceinline__ bf16_t f2bf(float x) { return (bf16_t)(cvt_pk_bf16(x, 0.f) & 0xffffu); }
; __device__ __forceinline__ void rw_phaseA(LAS unsigned char* lds, const RwCtx& X, int item) {
;     ...
;     int tid_s = threadIdx.x; asm volatile("" : "+v"(tid_s));
;     if (tid_s < 128) {
;         float x[64];
;         int zv = 0; asm volatile("" : "+v"(zv));
;         const LAS float* LABv = LAB + zv;
; #pragma unroll
;         for (int i = 0; i < 64; ++i) x[i] = XS[i * 129 + tid_s];
; #pragma unroll
;         for (int tt = 1; tt < 64; ++tt) { float a = x[tt];
; #pragma unroll
;             for (int s4 = 0; s4 < (tt + 3) / 4; ++s4) { const f32x4 l4 = *(const LAS f32x4*)(LABv + tt * 68 + s4 * 4);
;                 a += l4[0] * x[s4 * 4]; if (s4 * 4 + 1 < tt) a += l4[1] * x[s4 * 4 + 1]; if (s4 * 4 + 2 < tt) a += l4[2] * x[s4 * 4 + 2]; if (s4 * 4 + 3 < tt) a += l4[3] * x[s4 * 4 + 3]; }
;             x[tt] = a;
;     ...
;             __builtin_amdgcn_sched_barrier(0);
;     ...
;         }
;         LAS bf16_t* rowT = (tid_s < 64) ? (WT + tid_s * 72) : (UT + (tid_s - 64) * 72);
;         LAS bf16_t* colN = (tid_s < 64) ? (Wt + tid_s) : (Ut + (tid_s - 64));
; #pragma unroll
;         for (int g = 0; g < 8; ++g) { u32x4 o; o.x = cvt_pk_bf16(x[8 * g], x[8 * g + 1]); o.y = cvt_pk_bf16(x[8 * g + 2], x[8 * g + 3]); o.z = cvt_pk_bf16(x[8 * g + 4], x[8 * g + 5]); o.w = cvt_pk_bf16(x[8 * g + 6], x[8 * g + 7]);
;             *(LAS u32x4*)(rowT + 8 * g) = o; }
; #pragma unroll
;         for (int i = 0; i < 64; ++i) colN[i * 64] = f2bf(x[i]);
;     }
	v_fmac_f32_e32 v31, v32, v16
	v_mul_f32_e32 v13, v33, v17
	v_fmac_f32_e32 v31, v34, v18
	v_fmac_f32_e32 v13, v35, v19
	v_fmac_f32_e32 v31, v36, v20
	v_fmac_f32_e32 v13, v37, v21
	v_fmac_f32_e32 v31, v38, v22
	v_fmac_f32_e32 v13, v39, v23
	v_fmac_f32_e32 v31, v40, v24
	v_fmac_f32_e32 v13, v41, v25
	v_fmac_f32_e32 v31, v42, v26
	v_fmac_f32_e32 v13, v43, v27
	v_fmac_f32_e32 v31, v44, v28
	v_fmac_f32_e32 v13, v45, v29
	v_fmac_f32_e32 v31, v46, v30
	v_add_f32_e32 v31, v31, v13
	v_lshlrev_b32_e32 v6, 10, v1
	v_lshl_add_u32 v6, v0, 2, v6
	v_add_u32_e32 v6, 0x1d000, v6
	ds_write_b32 v6, v16 offset:0
	ds_write_b32 v6, v17 offset:64
	ds_write_b32 v6, v18 offset:128
	ds_write_b32 v6, v19 offset:192
	ds_write_b32 v6, v20 offset:256
	ds_write_b32 v6, v21 offset:320
	ds_write_b32 v6, v22 offset:384
	ds_write_b32 v6, v23 offset:448
	ds_write_b32 v6, v24 offset:512
	ds_write_b32 v6, v25 offset:576
	ds_write_b32 v6, v26 offset:640
	ds_write_b32 v6, v27 offset:704
	ds_write_b32 v6, v28 offset:768
	ds_write_b32 v6, v29 offset:832
	ds_write_b32 v6, v30 offset:896
	ds_write_b32 v6, v31 offset:960
	v_lshlrev_b32_e32 v7, 6, v0
	v_lshl_add_u32 v7, v1, 4, v7
	v_add_u32_e32 v7, 0x1d000, v7
	s_waitcnt lgkmcnt(0)
	ds_read_b128 v[80:83], v7 offset:0
	ds_read_b128 v[84:87], v7 offset:1024
	ds_read_b128 v[88:91], v7 offset:2048
	ds_read_b128 v[92:95], v7 offset:3072
	v_cmp_gt_u32_e32 vcc, 4, v2
	v_mul_u32_u24_e32 v8, 0x90, v11
	v_mov_b32_e32 v12, 0x17900
	v_mov_b32_e32 v13, 0x4800
	v_cndmask_b32_e32 v12, v12, v13, vcc
	v_add_u32_e32 v8, v8, v12
	v_lshl_add_u32 v8, v1, 3, v8
	v_lshlrev_b32_e32 v10, 1, v11
	v_mov_b32_e32 v12, 0x1f80
	v_mov_b32_e32 v13, 0
	v_cndmask_b32_e32 v12, v12, v13, vcc
	v_add_u32_e32 v10, v10, v12
	v_lshl_add_u32 v10, v1, 9, v10
	s_waitcnt lgkmcnt(0)
	v_mfma_f32_16x16x4_f32 v[120:123], v80, v64, 0
	v_mfma_f32_16x16x4_f32 v[120:123], v81, v65, v[120:123]
	v_mfma_f32_16x16x4_f32 v[120:123], v82, v66, v[120:123]
	v_mfma_f32_16x16x4_f32 v[120:123], v83, v67, v[120:123]
	s_nop 7
	s_nop 3
	v_mfma_f32_16x16x4_f32 v[68:71], v96, v120, v[68:71]
	v_mfma_f32_16x16x4_f32 v[68:71], v97, v121, v[68:71]
	v_mfma_f32_16x16x4_f32 v[68:71], v98, v122, v[68:71]
	v_mfma_f32_16x16x4_f32 v[68:71], v99, v123, v[68:71]
	v_mfma_f32_16x16x4_f32 v[72:75], v100, v120, v[72:75]
	v_mfma_f32_16x16x4_f32 v[72:75], v101, v121, v[72:75]
	v_mfma_f32_16x16x4_f32 v[72:75], v102, v122, v[72:75]
	v_mfma_f32_16x16x4_f32 v[72:75], v103, v123, v[72:75]
	v_mfma_f32_16x16x4_f32 v[76:79], v108, v120, v[76:79]
	v_mfma_f32_16x16x4_f32 v[76:79], v109, v121, v[76:79]
	v_mfma_f32_16x16x4_f32 v[76:79], v110, v122, v[76:79]
	v_mfma_f32_16x16x4_f32 v[76:79], v111, v123, v[76:79]
	s_nop 7
	s_nop 3
	v_mfma_f32_16x16x4_f32 v[124:127], v84, v68, 0
	v_mfma_f32_16x16x4_f32 v[124:127], v85, v69, v[124:127]
	v_mfma_f32_16x16x4_f32 v[124:127], v86, v70, v[124:127]
	v_mfma_f32_16x16x4_f32 v[124:127], v87, v71, v[124:127]
	s_nop 7
	s_nop 3
	v_mfma_f32_16x16x4_f32 v[72:75], v104, v124, v[72:75]
	v_mfma_f32_16x16x4_f32 v[72:75], v105, v125, v[72:75]
	v_mfma_f32_16x16x4_f32 v[72:75], v106, v126, v[72:75]
	v_mfma_f32_16x16x4_f32 v[72:75], v107, v127, v[72:75]
	v_mfma_f32_16x16x4_f32 v[76:79], v112, v124, v[76:79]
	v_mfma_f32_16x16x4_f32 v[76:79], v113, v125, v[76:79]
	v_mfma_f32_16x16x4_f32 v[76:79], v114, v126, v[76:79]
	v_mfma_f32_16x16x4_f32 v[76:79], v115, v127, v[76:79]
	s_nop 7
	s_nop 3
	v_mfma_f32_16x16x4_f32 v[128:131], v88, v72, 0
	v_mfma_f32_16x16x4_f32 v[128:131], v89, v73, v[128:131]
	v_mfma_f32_16x16x4_f32 v[128:131], v90, v74, v[128:131]
	v_mfma_f32_16x16x4_f32 v[128:131], v91, v75, v[128:131]
	s_nop 7
	s_nop 3
	v_mfma_f32_16x16x4_f32 v[76:79], v116, v128, v[76:79]
	v_mfma_f32_16x16x4_f32 v[76:79], v117, v129, v[76:79]
	v_mfma_f32_16x16x4_f32 v[76:79], v118, v130, v[76:79]
	v_mfma_f32_16x16x4_f32 v[76:79], v119, v131, v[76:79]
	s_nop 7
	s_nop 3
	v_mfma_f32_16x16x4_f32 v[132:135], v92, v76, 0
	v_mfma_f32_16x16x4_f32 v[132:135], v93, v77, v[132:135]
	v_mfma_f32_16x16x4_f32 v[132:135], v94, v78, v[132:135]
	v_mfma_f32_16x16x4_f32 v[132:135], v95, v79, v[132:135]
	s_nop 7
	s_nop 3
	v_cvt_pk_bf16_f32 v148, v120, v121
	v_cvt_pk_bf16_f32 v149, v122, v123
	v_cvt_pk_bf16_f32 v150, v124, v125
	v_cvt_pk_bf16_f32 v151, v126, v127
	v_cvt_pk_bf16_f32 v152, v128, v129
	v_cvt_pk_bf16_f32 v153, v130, v131
	v_cvt_pk_bf16_f32 v154, v132, v133
	v_cvt_pk_bf16_f32 v155, v134, v135
	ds_write_b64 v8, v[148:149] offset:0
	ds_write_b16 v10, v148 offset:0
	ds_write_b16_d16_hi v10, v148 offset:128
	ds_write_b16 v10, v149 offset:256
	ds_write_b16_d16_hi v10, v149 offset:384
	ds_write_b64 v8, v[150:151] offset:32
	ds_write_b16 v10, v150 offset:2048
	ds_write_b16_d16_hi v10, v150 offset:2176
	ds_write_b16 v10, v151 offset:2304
	ds_write_b16_d16_hi v10, v151 offset:2432
	ds_write_b64 v8, v[152:153] offset:64
	ds_write_b16 v10, v152 offset:4096
	ds_write_b16_d16_hi v10, v152 offset:4224
	ds_write_b16 v10, v153 offset:4352
	ds_write_b16_d16_hi v10, v153 offset:4480
	ds_write_b64 v8, v[154:155] offset:96
	ds_write_b16 v10, v154 offset:6144
	ds_write_b16_d16_hi v10, v154 offset:6272
	ds_write_b16 v10, v155 offset:6400
	ds_write_b16_d16_hi v10, v155 offset:6528
	s_branch .LBB0_720
